# attnB: removed denormal and inf guards of the log(1+e) expansion that cannot trigger for an argument in [1,2] (bit-identical output)
# speedup vs baseline: 1.0267x; 1.0065x over previous
.LBB0_512:
	v_cmp_le_i32_e32 vcc, s77, v133
	s_and_saveexec_b64 s[54:55], vcc
	s_cbranch_execz .LBB0_515
	v_cmp_gt_f32_e32 vcc, s69, v131
	s_cmp_eq_u64 vcc, exec
	s_cbranch_scc1 .LBB0_515
	v_add_u32_e32 v0, s81, v109
	v_add_u32_e32 v38, v0, v114
	ds_read_b128 v[34:37], v38
	v_add_u32_e32 v42, v0, v115
	ds_read_b128 v[134:137], v42 offset:4096
	ds_read_b128 v[38:41], v38 offset:4096
	v_add_u32_e32 v43, v0, v116
	v_add_u32_e32 v146, v0, v117
	v_add_u32_e32 v0, s79, v132
	v_add_u32_e32 v150, 64, v0
	v_cmp_ne_u32_e32 vcc, s79, v122
	s_waitcnt lgkmcnt(0)
	v_mfma_f32_32x32x16_bf16 v[50:65], v[34:37], v[74:77], 0
	ds_read_b128 v[34:37], v42
	v_add_u32_e32 v151, 0x41, v0
	v_cmp_lt_u32_e64 s[0:1], v150, v130
	v_cmp_lt_u32_e64 s[12:13], v151, v130
	s_or_b64 s[0:1], vcc, s[0:1]
	s_waitcnt lgkmcnt(0)
	v_mfma_f32_32x32x16_bf16 v[50:65], v[34:37], v[66:69], v[50:65]
	ds_read_b128 v[34:37], v43
	ds_read_b128 v[138:141], v43 offset:4096
	ds_read_b128 v[142:145], v146
	ds_read_b128 v[146:149], v146 offset:4096
	s_waitcnt lgkmcnt(0)
	v_mfma_f32_32x32x16_bf16 v[50:65], v[34:37], v[70:73], v[50:65]
	v_mfma_f32_32x32x16_bf16 v[50:65], v[142:145], v[78:81], v[50:65]
	v_mfma_f32_32x32x16_bf16 v[34:49], v[38:41], v[74:77], 0
	s_nop 10
	v_mul_f32_e32 v142, 0x3e000000, v50
	v_mul_f32_e32 v143, 0x3e000000, v51
	v_mul_f32_e64 v50, |v142|, s70
	v_mul_f32_e64 v51, |v143|, s70
	v_exp_f32_e32 v50, v50
	v_exp_f32_e32 v51, v51
	v_add_f32_e32 v50, 1.0, v50
	v_mfma_f32_32x32x16_bf16 v[34:49], v[134:137], v[66:69], v[34:49]
	v_add_f32_e32 v51, 1.0, v51
	v_max_f32_e32 v135, 0, v143
	v_log_f32_e32 v50, v50
	v_log_f32_e32 v51, v51
	v_mfma_f32_32x32x16_bf16 v[34:49], v[138:141], v[70:73], v[34:49]
	v_mul_f32_e32 v138, 0x3f317217, v50
	v_mul_f32_e32 v139, 0x3f317217, v51
	v_fma_f32 v138, v50, s72, -v138
	v_fma_f32 v139, v51, s72, -v139
	v_fmac_f32_e32 v138, 0x3377d1cf, v50
	v_fmac_f32_e32 v139, 0x3377d1cf, v51
	v_fmac_f32_e32 v138, 0x3f317217, v50
	v_fmac_f32_e32 v139, 0x3f317217, v51
	v_mov_b32_e32 v50, v138
	v_max_f32_e32 v134, 0, v142
	v_mov_b32_e32 v138, v139
	v_mov_b32_e32 v136, v138
	v_add_f32_e32 v135, v135, v136
	v_mul_f32_e32 v136, 0x3e000000, v52
	v_mul_f32_e64 v52, |v136|, s70
	v_exp_f32_e32 v137, v52
	v_add_f32_e32 v50, v134, v50
	v_cndmask_b32_e64 v50, 0, -v50, s[0:1]
	v_cndmask_b32_e64 v51, v129, v142, s[0:1]
	s_or_b64 s[0:1], vcc, s[12:13]
	v_add_f32_e32 v134, 0, v50
	v_cndmask_b32_e64 v52, 0, -v135, s[0:1]
	v_add_f32_e32 v137, 1.0, v137
	v_add_f32_e32 v135, v52, v134
	v_cndmask_b32_e64 v134, v129, v143, s[0:1]
	v_mfma_f32_32x32x16_bf16 v[34:49], v[146:149], v[78:81], v[34:49]
	s_nop 0
	v_log_f32_e32 v137, v137
	v_add_u32_e32 v138, 0x42, v0
	v_cmp_lt_u32_e64 s[12:13], v138, v130
	v_max_f32_e32 v138, 0, v136
	v_mul_f32_e32 v139, 0x3f317217, v137
	v_fma_f32 v139, v137, s72, -v139
	v_fmac_f32_e32 v139, 0x3377d1cf, v137
	v_fmac_f32_e32 v139, 0x3f317217, v137
	s_nop 2
	v_mul_f32_e32 v38, 0x3e000000, v38
	v_mul_f32_e32 v39, 0x3e000000, v39
	v_mov_b32_e32 v137, v139
	v_mul_f32_e32 v139, 0x3e000000, v53
	v_mul_f32_e64 v53, |v139|, s70
	v_add_f32_e32 v137, v138, v137
	v_exp_f32_e32 v138, v53
	s_or_b64 s[0:1], vcc, s[12:13]
	v_cndmask_b32_e64 v53, 0, -v137, s[0:1]
	v_add_f32_e32 v137, v53, v135
	v_cndmask_b32_e64 v135, v129, v136, s[0:1]
	v_add_f32_e32 v136, 1.0, v138
	v_mul_f32_e32 v40, 0x3e000000, v40
	v_mul_f32_e32 v41, 0x3e000000, v41
	v_log_f32_e32 v136, v136
	v_add_u32_e32 v138, 0x43, v0
	v_cmp_lt_u32_e64 s[12:13], v138, v130
	v_max_f32_e32 v138, 0, v139
	v_mul_f32_e32 v140, 0x3f317217, v136
	v_fma_f32 v140, v136, s72, -v140
	v_fmac_f32_e32 v140, 0x3377d1cf, v136
	v_fmac_f32_e32 v140, 0x3f317217, v136
	s_nop 1
	v_mov_b32_e32 v136, v140
	v_mul_f32_e32 v140, 0x3e000000, v54
	v_mul_f32_e64 v54, |v140|, s70
	v_exp_f32_e32 v141, v54
	v_add_f32_e32 v136, v138, v136
	s_or_b64 s[0:1], vcc, s[12:13]
	v_cndmask_b32_e64 v54, 0, -v136, s[0:1]
	v_add_f32_e32 v138, v54, v137
	v_add_f32_e32 v137, 1.0, v141
	v_cndmask_b32_e64 v136, v129, v139, s[0:1]
	s_nop 1
	v_log_f32_e32 v137, v137
	v_add_u32_e32 v139, 0x48, v0
	v_cmp_lt_u32_e64 s[12:13], v139, v130
	v_max_f32_e32 v139, 0, v140
	v_mul_f32_e32 v141, 0x3f317217, v137
	v_fma_f32 v141, v137, s72, -v141
	v_fmac_f32_e32 v141, 0x3377d1cf, v137
	v_fmac_f32_e32 v141, 0x3f317217, v137
	s_nop 1
	v_mov_b32_e32 v137, v141
	v_add_f32_e32 v137, v139, v137
	v_mul_f32_e32 v139, 0x3e000000, v55
	v_mul_f32_e64 v55, |v139|, s70
	v_exp_f32_e32 v141, v55
	s_or_b64 s[0:1], vcc, s[12:13]
	v_cndmask_b32_e64 v55, 0, -v137, s[0:1]
	v_cndmask_b32_e64 v137, v129, v140, s[0:1]
	v_add_f32_e32 v140, 1.0, v141
	v_add_f32_e32 v142, 0, v55
	s_nop 0
	v_log_f32_e32 v140, v140
	v_add_u32_e32 v141, 0x49, v0
	v_cmp_lt_u32_e64 s[12:13], v141, v130
	v_max_f32_e32 v141, 0, v139
	v_mul_f32_e32 v143, 0x3f317217, v140
	v_fma_f32 v143, v140, s72, -v143
	v_fmac_f32_e32 v143, 0x3377d1cf, v140
	v_fmac_f32_e32 v143, 0x3f317217, v140
	s_nop 1
	v_mov_b32_e32 v140, v143
	v_add_f32_e32 v140, v141, v140
	v_mul_f32_e32 v141, 0x3e000000, v56
	v_mul_f32_e64 v56, |v141|, s70
	v_exp_f32_e32 v143, v56
	s_or_b64 s[0:1], vcc, s[12:13]
	v_cndmask_b32_e64 v56, 0, -v140, s[0:1]
	v_add_f32_e32 v140, v56, v142
	v_add_f32_e32 v142, 1.0, v143
	v_cndmask_b32_e64 v139, v129, v139, s[0:1]
	s_nop 1
	v_log_f32_e32 v142, v142
	v_add_u32_e32 v143, 0x4a, v0
	v_cmp_lt_u32_e64 s[12:13], v143, v130
	v_max_f32_e32 v143, 0, v141
	v_mul_f32_e32 v144, 0x3f317217, v142
	v_fma_f32 v144, v142, s72, -v144
	v_fmac_f32_e32 v144, 0x3377d1cf, v142
	v_fmac_f32_e32 v144, 0x3f317217, v142
	s_nop 1
	v_mov_b32_e32 v142, v144
	v_mul_f32_e32 v144, 0x3e000000, v57
	v_mul_f32_e64 v57, |v144|, s70
	v_add_f32_e32 v142, v143, v142
	v_exp_f32_e32 v143, v57
	s_or_b64 s[0:1], vcc, s[12:13]
	v_cndmask_b32_e64 v57, 0, -v142, s[0:1]
	v_add_f32_e32 v142, v57, v140
	v_cndmask_b32_e64 v140, v129, v141, s[0:1]
	v_add_f32_e32 v141, 1.0, v143
	s_nop 1
	v_log_f32_e32 v141, v141
	v_add_u32_e32 v143, 0x4b, v0
	v_cmp_lt_u32_e64 s[12:13], v143, v130
	v_max_f32_e32 v143, 0, v144
	v_mul_f32_e32 v145, 0x3f317217, v141
	v_fma_f32 v145, v141, s72, -v145
	v_fmac_f32_e32 v145, 0x3377d1cf, v141
	v_fmac_f32_e32 v145, 0x3f317217, v141
	s_nop 1
	v_mov_b32_e32 v141, v145
	v_mul_f32_e32 v145, 0x3e000000, v58
	v_mul_f32_e64 v58, |v145|, s70
	v_exp_f32_e32 v146, v58
	v_add_f32_e32 v141, v143, v141
	s_or_b64 s[0:1], vcc, s[12:13]
	v_cndmask_b32_e64 v58, 0, -v141, s[0:1]
	v_add_f32_e32 v143, v58, v142
	v_add_f32_e32 v142, 1.0, v146
	v_cndmask_b32_e64 v141, v129, v144, s[0:1]
	s_nop 1
	v_log_f32_e32 v142, v142
	v_add_u32_e32 v144, 0x50, v0
	v_cmp_lt_u32_e64 s[12:13], v144, v130
	v_max_f32_e32 v144, 0, v145
	v_mul_f32_e32 v146, 0x3f317217, v142
	v_fma_f32 v146, v142, s72, -v146
	v_fmac_f32_e32 v146, 0x3377d1cf, v142
	v_fmac_f32_e32 v146, 0x3f317217, v142
	s_nop 1
	v_mov_b32_e32 v142, v146
	v_add_f32_e32 v142, v144, v142
	v_mul_f32_e32 v144, 0x3e000000, v59
	v_mul_f32_e64 v59, |v144|, s70
	v_exp_f32_e32 v146, v59
	s_or_b64 s[0:1], vcc, s[12:13]
	v_cndmask_b32_e64 v59, 0, -v142, s[0:1]
	v_cndmask_b32_e64 v142, v129, v145, s[0:1]
	v_add_f32_e32 v145, 1.0, v146
	v_add_f32_e32 v147, 0, v59
	s_nop 0
	v_log_f32_e32 v145, v145
	v_add_u32_e32 v146, 0x51, v0
	v_cmp_lt_u32_e64 s[12:13], v146, v130
	v_max_f32_e32 v146, 0, v144
	v_mul_f32_e32 v148, 0x3f317217, v145
	v_fma_f32 v148, v145, s72, -v148
	v_fmac_f32_e32 v148, 0x3377d1cf, v145
	v_fmac_f32_e32 v148, 0x3f317217, v145
	s_nop 1
	v_mov_b32_e32 v145, v148
	v_add_f32_e32 v145, v146, v145
	v_mul_f32_e32 v146, 0x3e000000, v60
	v_mul_f32_e64 v60, |v146|, s70
	v_exp_f32_e32 v148, v60
	s_or_b64 s[0:1], vcc, s[12:13]
	v_cndmask_b32_e64 v60, 0, -v145, s[0:1]
	v_add_f32_e32 v145, v60, v147
	v_add_f32_e32 v147, 1.0, v148
	v_cndmask_b32_e64 v144, v129, v144, s[0:1]
	s_nop 1
	v_log_f32_e32 v147, v147
	v_add_u32_e32 v148, 0x52, v0
	v_cmp_lt_u32_e64 s[12:13], v148, v130
	v_max_f32_e32 v148, 0, v146
	v_mul_f32_e32 v149, 0x3f317217, v147
	v_fma_f32 v149, v147, s72, -v149
	v_fmac_f32_e32 v149, 0x3377d1cf, v147
	v_fmac_f32_e32 v149, 0x3f317217, v147
	s_nop 1
	v_mov_b32_e32 v147, v149
	v_mul_f32_e32 v149, 0x3e000000, v61
	v_mul_f32_e64 v61, |v149|, s70
	v_add_f32_e32 v147, v148, v147
	v_exp_f32_e32 v148, v61
	s_or_b64 s[0:1], vcc, s[12:13]
	v_cndmask_b32_e64 v61, 0, -v147, s[0:1]
	v_add_f32_e32 v147, v61, v145
	v_cndmask_b32_e64 v145, v129, v146, s[0:1]
	v_add_f32_e32 v146, 1.0, v148
	s_nop 1
	v_log_f32_e32 v146, v146
	v_add_u32_e32 v148, 0x53, v0
	v_cmp_lt_u32_e64 s[12:13], v148, v130
	v_max_f32_e32 v148, 0, v149
	v_mul_f32_e32 v150, 0x3f317217, v146
	v_fma_f32 v150, v146, s72, -v150
	v_fmac_f32_e32 v150, 0x3377d1cf, v146
	v_fmac_f32_e32 v150, 0x3f317217, v146
	s_nop 1
	v_mov_b32_e32 v146, v150
	v_mul_f32_e32 v150, 0x3e000000, v62
	v_mul_f32_e64 v62, |v150|, s70
	v_exp_f32_e32 v151, v62
	v_add_f32_e32 v146, v148, v146
	s_or_b64 s[0:1], vcc, s[12:13]
	v_cndmask_b32_e64 v62, 0, -v146, s[0:1]
	v_add_f32_e32 v148, v62, v147
	v_add_f32_e32 v147, 1.0, v151
	v_cndmask_b32_e64 v146, v129, v149, s[0:1]
	s_nop 1
	v_log_f32_e32 v147, v147
	v_add_u32_e32 v149, 0x58, v0
	v_cmp_lt_u32_e64 s[12:13], v149, v130
	v_max_f32_e32 v149, 0, v150
	v_mul_f32_e32 v151, 0x3f317217, v147
	v_fma_f32 v151, v147, s72, -v151
	v_fmac_f32_e32 v151, 0x3377d1cf, v147
	v_fmac_f32_e32 v151, 0x3f317217, v147
	s_nop 1
	v_mov_b32_e32 v147, v151
	v_add_f32_e32 v147, v149, v147
	v_mul_f32_e32 v149, 0x3e000000, v63
	v_mul_f32_e64 v63, |v149|, s70
	v_exp_f32_e32 v151, v63
	s_or_b64 s[0:1], vcc, s[12:13]
	v_cndmask_b32_e64 v63, 0, -v147, s[0:1]
	v_cndmask_b32_e64 v147, v129, v150, s[0:1]
	v_add_f32_e32 v150, 1.0, v151
	v_add_f32_e32 v152, 0, v63
	s_nop 0
	v_log_f32_e32 v150, v150
	v_add_u32_e32 v151, 0x59, v0
	v_cmp_lt_u32_e64 s[12:13], v151, v130
	v_max_f32_e32 v151, 0, v149
	v_mul_f32_e32 v153, 0x3f317217, v150
	v_fma_f32 v153, v150, s72, -v153
	v_fmac_f32_e32 v153, 0x3377d1cf, v150
	v_fmac_f32_e32 v153, 0x3f317217, v150
	s_nop 1
	v_mov_b32_e32 v150, v153
	v_add_f32_e32 v150, v151, v150
	v_mul_f32_e32 v151, 0x3e000000, v64
	v_mul_f32_e64 v64, |v151|, s70
	v_exp_f32_e32 v153, v64
	s_or_b64 s[0:1], vcc, s[12:13]
	v_cndmask_b32_e64 v64, 0, -v150, s[0:1]
	v_add_f32_e32 v150, v64, v152
	v_add_f32_e32 v152, 1.0, v153
	v_cndmask_b32_e64 v149, v129, v149, s[0:1]
	s_nop 1
	v_log_f32_e32 v152, v152
	v_add_u32_e32 v153, 0x5a, v0
	v_cmp_lt_u32_e64 s[12:13], v153, v130
	v_max_f32_e32 v153, 0, v151
	v_mul_f32_e32 v155, 0x3f317217, v152
	v_fma_f32 v155, v152, s72, -v155
	v_fmac_f32_e32 v155, 0x3377d1cf, v152
	v_fmac_f32_e32 v155, 0x3f317217, v152
	s_nop 1
	v_mov_b32_e32 v152, v155
	v_mul_f32_e32 v155, 0x3e000000, v65
	v_mul_f32_e64 v65, |v155|, s70
	v_add_f32_e32 v152, v153, v152
	v_exp_f32_e32 v153, v65
	s_or_b64 s[0:1], vcc, s[12:13]
	v_cndmask_b32_e64 v65, 0, -v152, s[0:1]
	v_add_f32_e32 v152, v65, v150
	v_cndmask_b32_e64 v150, v129, v151, s[0:1]
	v_add_f32_e32 v151, 1.0, v153
	s_nop 1
	v_log_f32_e32 v151, v151
	v_add_u32_e32 v153, 0x5b, v0
	v_cmp_lt_u32_e64 s[12:13], v153, v130
	v_max_f32_e32 v153, 0, v155
	v_mul_f32_e32 v156, 0x3f317217, v151
	v_fma_f32 v156, v151, s72, -v156
	v_fmac_f32_e32 v156, 0x3377d1cf, v151
	v_fmac_f32_e32 v156, 0x3f317217, v151
	s_nop 1
	v_mov_b32_e32 v151, v156
	v_mul_f32_e32 v156, 0x3e000000, v34
	v_mul_f32_e64 v34, |v156|, s70
	v_exp_f32_e32 v34, v34
	v_add_f32_e32 v151, v153, v151
	s_or_b64 s[0:1], vcc, s[12:13]
	v_cndmask_b32_e64 v151, 0, -v151, s[0:1]
	v_add_f32_e32 v34, 1.0, v34
	v_add_f32_e32 v153, v151, v152
	v_cndmask_b32_e64 v152, v129, v155, s[0:1]
	s_nop 1
	v_log_f32_e32 v34, v34
	v_add_u32_e32 v155, 0x60, v0
	v_cmp_lt_u32_e64 s[12:13], v155, v130
	v_max_f32_e32 v155, 0, v156
	v_mul_f32_e32 v157, 0x3f317217, v34
	v_fma_f32 v157, v34, s72, -v157
	v_fmac_f32_e32 v157, 0x3377d1cf, v34
	v_fmac_f32_e32 v157, 0x3f317217, v34
	s_nop 1
	v_mov_b32_e32 v34, v157
	v_add_f32_e32 v34, v155, v34
	v_mul_f32_e32 v155, 0x3e000000, v35
	v_mul_f32_e64 v35, |v155|, s70
	v_exp_f32_e32 v157, v35
	s_or_b64 s[0:1], vcc, s[12:13]
	v_cndmask_b32_e64 v35, v129, v156, s[0:1]
	v_cndmask_b32_e64 v34, 0, -v34, s[0:1]
	v_add_f32_e32 v156, 1.0, v157
	v_add_f32_e32 v158, 0, v34
	s_nop 0
	v_log_f32_e32 v156, v156
	v_add_u32_e32 v157, 0x61, v0
	v_cmp_lt_u32_e64 s[12:13], v157, v130
	v_max_f32_e32 v157, 0, v155
	v_mul_f32_e32 v159, 0x3f317217, v156
	v_fma_f32 v159, v156, s72, -v159
	v_fmac_f32_e32 v159, 0x3377d1cf, v156
	v_fmac_f32_e32 v159, 0x3f317217, v156
	s_nop 1
	v_mov_b32_e32 v156, v159
	v_add_f32_e32 v156, v157, v156
	v_mul_f32_e32 v157, 0x3e000000, v36
	v_mul_f32_e64 v36, |v157|, s70
	v_exp_f32_e32 v159, v36
	s_or_b64 s[0:1], vcc, s[12:13]
	v_cndmask_b32_e64 v36, 0, -v156, s[0:1]
	v_add_f32_e32 v156, v36, v158
	v_add_f32_e32 v158, 1.0, v159
	v_cndmask_b32_e64 v155, v129, v155, s[0:1]
	s_nop 1
	v_log_f32_e32 v158, v158
	v_add_u32_e32 v159, 0x62, v0
	v_cmp_lt_u32_e64 s[12:13], v159, v130
	v_max_f32_e32 v159, 0, v157
	v_mul_f32_e32 v160, 0x3f317217, v158
	v_fma_f32 v160, v158, s72, -v160
	v_fmac_f32_e32 v160, 0x3377d1cf, v158
	v_fmac_f32_e32 v160, 0x3f317217, v158
	s_nop 1
	v_mov_b32_e32 v158, v160
	v_add_f32_e32 v158, v159, v158
	v_mul_f32_e32 v159, 0x3e000000, v37
	v_mul_f32_e64 v37, |v159|, s70
	v_exp_f32_e32 v160, v37
	s_or_b64 s[0:1], vcc, s[12:13]
	v_cndmask_b32_e64 v37, 0, -v158, s[0:1]
	v_add_f32_e32 v158, v37, v156
	v_cndmask_b32_e64 v156, v129, v157, s[0:1]
	v_add_f32_e32 v157, 1.0, v160
	s_nop 1
	v_log_f32_e32 v157, v157
	v_add_u32_e32 v160, 0x63, v0
	v_cmp_lt_u32_e64 s[12:13], v160, v130
	v_max_f32_e32 v160, 0, v159
	v_mul_f32_e32 v161, 0x3f317217, v157
	v_fma_f32 v161, v157, s72, -v161
	v_fmac_f32_e32 v161, 0x3377d1cf, v157
	v_fmac_f32_e32 v161, 0x3f317217, v157
	s_nop 1
	v_mov_b32_e32 v157, v161
	v_add_f32_e32 v157, v160, v157
	v_mul_f32_e64 v160, |v38|, s70
	v_exp_f32_e32 v160, v160
	s_or_b64 s[0:1], vcc, s[12:13]
	v_cndmask_b32_e64 v157, 0, -v157, s[0:1]
	v_cndmask_b32_e64 v159, v129, v159, s[0:1]
	v_add_f32_e32 v160, 1.0, v160
	v_add_f32_e32 v158, v157, v158
	s_nop 0
	v_log_f32_e32 v160, v160
	v_add_u32_e32 v161, 0x68, v0
	v_cmp_lt_u32_e64 s[12:13], v161, v130
	v_max_f32_e32 v161, 0, v38
	v_mul_f32_e32 v162, 0x3f317217, v160
	v_fma_f32 v162, v160, s72, -v162
	v_fmac_f32_e32 v162, 0x3377d1cf, v160
	v_fmac_f32_e32 v162, 0x3f317217, v160
	s_nop 1
	v_mov_b32_e32 v160, v162
	v_add_f32_e32 v160, v161, v160
	v_mul_f32_e64 v161, |v39|, s70
	v_exp_f32_e32 v161, v161
	s_or_b64 s[0:1], vcc, s[12:13]
	v_cndmask_b32_e64 v163, v129, v38, s[0:1]
	v_cndmask_b32_e64 v160, 0, -v160, s[0:1]
	v_add_f32_e32 v38, 1.0, v161
	v_add_f32_e32 v162, 0, v160
	s_nop 0
	v_log_f32_e32 v38, v38
	v_add_u32_e32 v161, 0x69, v0
	v_cmp_lt_u32_e64 s[12:13], v161, v130
	v_max_f32_e32 v161, 0, v39
	v_mul_f32_e32 v164, 0x3f317217, v38
	v_fma_f32 v164, v38, s72, -v164
	v_fmac_f32_e32 v164, 0x3377d1cf, v38
	v_fmac_f32_e32 v164, 0x3f317217, v38
	s_nop 1
	v_mov_b32_e32 v38, v164
	v_add_f32_e32 v38, v161, v38
	v_mul_f32_e64 v161, |v40|, s70
	v_exp_f32_e32 v161, v161
	s_or_b64 s[0:1], vcc, s[12:13]
	v_cndmask_b32_e64 v164, 0, -v38, s[0:1]
	v_add_f32_e32 v38, v164, v162
	v_cndmask_b32_e64 v162, v129, v39, s[0:1]
	v_add_f32_e32 v39, 1.0, v161
	s_nop 1
	v_log_f32_e32 v39, v39
	v_add_u32_e32 v161, 0x6a, v0
	v_cmp_lt_u32_e64 s[12:13], v161, v130
	v_max_f32_e32 v161, 0, v40
	v_mul_f32_e32 v165, 0x3f317217, v39
	v_fma_f32 v165, v39, s72, -v165
	v_fmac_f32_e32 v165, 0x3377d1cf, v39
	v_fmac_f32_e32 v165, 0x3f317217, v39
	s_nop 1
	v_mov_b32_e32 v39, v165
	v_add_f32_e32 v39, v161, v39
	v_mul_f32_e64 v161, |v41|, s70
	v_exp_f32_e32 v161, v161
	s_or_b64 s[0:1], vcc, s[12:13]
	v_cndmask_b32_e64 v165, 0, -v39, s[0:1]
	v_cndmask_b32_e64 v166, v129, v40, s[0:1]
	v_add_f32_e32 v39, 1.0, v161
	v_add_f32_e32 v38, v165, v38
	s_nop 0
	v_log_f32_e32 v39, v39
	v_add_u32_e32 v40, 0x6b, v0
	v_cmp_lt_u32_e64 s[12:13], v40, v130
	v_max_f32_e32 v40, 0, v41
	v_mul_f32_e32 v161, 0x3f317217, v39
	v_fma_f32 v161, v39, s72, -v161
	v_fmac_f32_e32 v161, 0x3377d1cf, v39
	v_fmac_f32_e32 v161, 0x3f317217, v39
	s_nop 1
	v_mov_b32_e32 v39, v161
	v_add_f32_e32 v39, v40, v39
	v_mul_f32_e32 v40, 0x3e000000, v42
	v_mul_f32_e64 v42, |v40|, s70
	v_exp_f32_e32 v42, v42
	s_or_b64 s[0:1], vcc, s[12:13]
	v_cndmask_b32_e64 v161, 0, -v39, s[0:1]
	v_add_f32_e32 v167, v161, v38
	v_add_f32_e32 v38, 1.0, v42
	v_cndmask_b32_e64 v168, v129, v41, s[0:1]
	s_nop 1
	v_log_f32_e32 v38, v38
	v_add_u32_e32 v39, 0x70, v0
	v_cmp_lt_u32_e64 s[12:13], v39, v130
	v_max_f32_e32 v39, 0, v40
	v_mul_f32_e32 v41, 0x3f317217, v38
	v_fma_f32 v41, v38, s72, -v41
	v_fmac_f32_e32 v41, 0x3377d1cf, v38
	v_fmac_f32_e32 v41, 0x3f317217, v38
	s_nop 1
	v_mov_b32_e32 v38, v41
	v_add_f32_e32 v38, v39, v38
	v_mul_f32_e32 v39, 0x3e000000, v43
	v_mul_f32_e64 v41, |v39|, s70
	v_exp_f32_e32 v41, v41
	s_or_b64 s[0:1], vcc, s[12:13]
	v_cndmask_b32_e64 v170, v129, v40, s[0:1]
	v_cndmask_b32_e64 v169, 0, -v38, s[0:1]
	v_add_f32_e32 v40, 1.0, v41
	v_add_f32_e32 v38, 0, v169
	s_nop 0
	v_log_f32_e32 v40, v40
	v_add_u32_e32 v41, 0x71, v0
	v_cmp_lt_u32_e64 s[12:13], v41, v130
	v_max_f32_e32 v41, 0, v39
	v_mul_f32_e32 v42, 0x3f317217, v40
	v_fma_f32 v42, v40, s72, -v42
	v_fmac_f32_e32 v42, 0x3377d1cf, v40
	v_fmac_f32_e32 v42, 0x3f317217, v40
	s_nop 1
	v_mov_b32_e32 v40, v42
	v_add_f32_e32 v40, v41, v40
	v_mul_f32_e32 v41, 0x3e000000, v44
	v_mul_f32_e64 v42, |v41|, s70
	v_exp_f32_e32 v42, v42
	s_or_b64 s[0:1], vcc, s[12:13]
	v_cndmask_b32_e64 v172, v129, v39, s[0:1]
	v_cndmask_b32_e64 v171, 0, -v40, s[0:1]
	v_add_f32_e32 v39, 1.0, v42
	v_add_f32_e32 v38, v171, v38
	s_nop 0
	v_log_f32_e32 v39, v39
	v_add_u32_e32 v40, 0x72, v0
	v_cmp_lt_u32_e64 s[12:13], v40, v130
	v_max_f32_e32 v40, 0, v41
	v_mul_f32_e32 v42, 0x3f317217, v39
	v_fma_f32 v42, v39, s72, -v42
	v_fmac_f32_e32 v42, 0x3377d1cf, v39
	v_fmac_f32_e32 v42, 0x3f317217, v39
	s_nop 1
	v_mov_b32_e32 v39, v42
	v_add_f32_e32 v39, v40, v39
	v_mul_f32_e32 v40, 0x3e000000, v45
	v_mul_f32_e64 v42, |v40|, s70
	v_exp_f32_e32 v42, v42
	s_or_b64 s[0:1], vcc, s[12:13]
	v_cndmask_b32_e64 v173, 0, -v39, s[0:1]
	v_cndmask_b32_e64 v174, v129, v41, s[0:1]
	v_add_f32_e32 v39, 1.0, v42
	v_add_f32_e32 v38, v173, v38
	s_nop 0
	v_log_f32_e32 v39, v39
	v_add_u32_e32 v41, 0x73, v0
	v_cmp_lt_u32_e64 s[12:13], v41, v130
	v_max_f32_e32 v41, 0, v40
	v_mul_f32_e32 v42, 0x3f317217, v39
	v_fma_f32 v42, v39, s72, -v42
	v_fmac_f32_e32 v42, 0x3377d1cf, v39
	v_fmac_f32_e32 v42, 0x3f317217, v39
	s_nop 1
	v_mov_b32_e32 v39, v42
	v_add_f32_e32 v39, v41, v39
	v_mul_f32_e32 v41, 0x3e000000, v46
	v_mul_f32_e64 v42, |v41|, s70
	v_exp_f32_e32 v42, v42
	s_or_b64 s[0:1], vcc, s[12:13]
	v_cndmask_b32_e64 v46, 0, -v39, s[0:1]
	v_add_f32_e32 v175, v46, v38
	v_add_f32_e32 v38, 1.0, v42
	v_cndmask_b32_e64 v176, v129, v40, s[0:1]
	s_nop 1
	v_log_f32_e32 v38, v38
	v_add_u32_e32 v39, 0x78, v0
	v_cmp_lt_u32_e64 s[12:13], v39, v130
	v_max_f32_e32 v39, 0, v41
	v_mul_f32_e32 v40, 0x3f317217, v38
	v_fma_f32 v40, v38, s72, -v40
	v_fmac_f32_e32 v40, 0x3377d1cf, v38
	v_fmac_f32_e32 v40, 0x3f317217, v38
	s_nop 1
	v_mov_b32_e32 v38, v40
	v_add_f32_e32 v38, v39, v38
	v_mul_f32_e32 v39, 0x3e000000, v47
	v_mul_f32_e64 v40, |v39|, s70
	v_exp_f32_e32 v40, v40
	s_or_b64 s[0:1], vcc, s[12:13]
	v_cndmask_b32_e64 v177, 0, -v38, s[0:1]
	v_cndmask_b32_e64 v178, v129, v41, s[0:1]
	v_add_f32_e32 v40, 1.0, v40
	v_add_f32_e32 v38, 0, v177
	s_nop 0
	v_log_f32_e32 v40, v40
	v_add_u32_e32 v41, 0x79, v0
	v_cmp_lt_u32_e64 s[12:13], v41, v130
	v_max_f32_e32 v41, 0, v39
	v_mul_f32_e32 v42, 0x3f317217, v40
	v_fma_f32 v42, v40, s72, -v42
	v_fmac_f32_e32 v42, 0x3377d1cf, v40
	v_fmac_f32_e32 v42, 0x3f317217, v40
	s_nop 1
	v_mov_b32_e32 v40, v42
	v_add_f32_e32 v40, v41, v40
	v_mul_f32_e32 v41, 0x3e000000, v48
	v_mul_f32_e64 v42, |v41|, s70
	v_exp_f32_e32 v42, v42
	s_or_b64 s[0:1], vcc, s[12:13]
	v_cndmask_b32_e64 v180, v129, v39, s[0:1]
	v_cndmask_b32_e64 v179, 0, -v40, s[0:1]
	v_add_f32_e32 v39, 1.0, v42
	v_add_f32_e32 v38, v179, v38
	s_nop 0
	v_log_f32_e32 v39, v39
	v_add_u32_e32 v40, 0x7a, v0
	v_cmp_lt_u32_e64 s[12:13], v40, v130
	v_max_f32_e32 v40, 0, v41
	v_mul_f32_e32 v42, 0x3f317217, v39
	v_fma_f32 v42, v39, s72, -v42
	v_fmac_f32_e32 v42, 0x3377d1cf, v39
	v_fmac_f32_e32 v42, 0x3f317217, v39
	v_add_u32_e32 v0, 0x7b, v0
	s_nop 0
	v_mov_b32_e32 v39, v42
	v_add_f32_e32 v39, v40, v39
	v_mul_f32_e32 v40, 0x3e000000, v49
	v_mul_f32_e64 v42, |v40|, s70
	v_exp_f32_e32 v42, v42
	s_or_b64 s[0:1], vcc, s[12:13]
	v_cndmask_b32_e64 v181, 0, -v39, s[0:1]
	v_cndmask_b32_e64 v182, v129, v41, s[0:1]
	v_add_f32_e32 v39, 1.0, v42
	v_cmp_lt_u32_e64 s[12:13], v0, v130
	v_max_f32_e32 v0, 0, v40
	v_log_f32_e32 v39, v39
	s_or_b64 vcc, vcc, s[12:13]
	v_add_f32_e32 v38, v181, v38
	v_cndmask_b32_e32 v184, v129, v40, vcc
	v_mul_f32_e32 v41, 0x3f317217, v39
	v_fma_f32 v41, v39, s72, -v41
	v_fmac_f32_e32 v41, 0x3377d1cf, v39
	v_fmac_f32_e32 v41, 0x3f317217, v39
	s_nop 1
	v_mov_b32_e32 v39, v41
	v_add_f32_e32 v0, v0, v39
	v_cndmask_b32_e64 v0, 0, -v0, vcc
	v_add_f32_e32 v183, v0, v38
	v_add_f32_e32 v47, v183, v175
	v_add_f32_e32 v48, v167, v47
	v_add_f32_e32 v49, v158, v48
	v_add_f32_e32 v38, v153, v49
	v_add_f32_e32 v39, v148, v38
	v_cmp_lt_i32_e32 vcc, v126, v127
	v_add_f32_e32 v40, v143, v39
	v_add_f32_e32 v185, v138, v40
	v_cndmask_b32_e32 v41, v125, v126, vcc
	v_lshlrev_b32_e32 v41, 2, v41
	ds_bpermute_b32 v186, v41, v185
	ds_bpermute_b32 v42, v41, v40
	ds_bpermute_b32 v43, v41, v39
	ds_bpermute_b32 v44, v41, v38
	ds_bpermute_b32 v187, v41, v49
	ds_bpermute_b32 v188, v41, v48
	ds_bpermute_b32 v189, v41, v47
	ds_bpermute_b32 v190, v41, v183
	v_sub_f32_e32 v41, v185, v138
	s_waitcnt lgkmcnt(0)
	v_cndmask_b32_e64 v45, v42, v186, s[8:9]
	v_add_f32_e32 v41, v45, v41
	v_sub_f32_e32 v40, v40, v143
	v_cndmask_b32_e64 v42, v43, v42, s[8:9]
	v_sub_f32_e32 v39, v39, v148
	v_cndmask_b32_e64 v43, v44, v43, s[8:9]
	v_add_f32_e32 v41, v131, v41
	v_add_f32_e32 v40, v42, v40
	v_add_f32_e32 v39, v43, v39
	v_add_f32_e32 v41, v54, v41
	v_add_f32_e32 v40, v131, v40
	v_add_f32_e32 v39, v131, v39
	v_add_f32_e32 v45, v136, v41
	v_add_f32_e32 v41, v53, v41
	v_add_f32_e32 v40, v58, v40
	v_add_f32_e32 v39, v62, v39
	v_add_f32_e32 v53, v135, v41
	v_add_f32_e32 v41, v52, v41
	v_add_f32_e32 v42, v141, v40
	v_add_f32_e32 v40, v57, v40
	v_add_f32_e32 v43, v146, v39
	v_add_f32_e32 v39, v61, v39
	v_add_f32_e32 v52, v134, v41
	v_add_f32_e32 v41, v50, v41
	v_add_f32_e32 v50, v140, v40
	v_add_f32_e32 v40, v56, v40
	v_add_f32_e32 v54, v145, v39
	v_add_f32_e32 v39, v60, v39
	v_add_f32_e32 v41, v51, v41
	v_add_f32_e32 v51, v139, v40
	v_add_f32_e32 v40, v55, v40
	v_add_f32_e32 v55, v144, v39
	v_add_f32_e32 v39, v59, v39
	v_add_f32_e32 v39, v142, v39
	v_mul_f32_e32 v39, 0x3fb8aa3b, v39
	v_exp_f32_e32 v56, v39
	v_sub_f32_e32 v38, v38, v153
	v_cndmask_b32_e64 v39, v187, v44, s[8:9]
	v_add_f32_e32 v38, v39, v38
	v_add_f32_e32 v38, v131, v38
	v_add_f32_e32 v38, v151, v38
	v_add_f32_e32 v39, v152, v38
	v_mul_f32_e32 v39, 0x3fb8aa3b, v39
	v_add_f32_e32 v38, v65, v38
	v_mul_f32_e32 v52, 0x3fb8aa3b, v52
	v_mul_f32_e32 v41, 0x3fb8aa3b, v41
	v_mul_f32_e32 v42, 0x3fb8aa3b, v42
	v_mul_f32_e32 v50, 0x3fb8aa3b, v50
	v_exp_f32_e32 v57, v39
	v_add_f32_e32 v39, v150, v38
	v_exp_f32_e32 v52, v52
	v_exp_f32_e32 v41, v41
	v_exp_f32_e32 v42, v42
	v_exp_f32_e32 v50, v50
	v_mul_f32_e32 v39, 0x3fb8aa3b, v39
	v_add_f32_e32 v38, v64, v38
	v_exp_f32_e32 v58, v39
	v_add_f32_e32 v39, v149, v38
	v_add_f32_e32 v38, v63, v38
	v_add_f32_e32 v38, v147, v38
	v_mul_f32_e32 v38, 0x3fb8aa3b, v38
	v_exp_f32_e32 v59, v38
	v_cvt_pk_bf16_f32 v38, v41, v52
	v_cvt_pk_bf16_f32 v41, v50, v42
	v_sub_f32_e32 v49, v49, v158
	v_cndmask_b32_e64 v50, v188, v187, s[8:9]
	v_add_f32_e32 v49, v50, v49
	v_add_f32_e32 v49, v131, v49
	v_add_f32_e32 v49, v157, v49
	v_mul_f32_e32 v45, 0x3fb8aa3b, v45
	v_mul_f32_e32 v53, 0x3fb8aa3b, v53
	v_add_f32_e32 v37, v37, v49
	v_exp_f32_e32 v45, v45
	v_exp_f32_e32 v53, v53
	v_add_f32_e32 v36, v36, v37
	v_add_f32_e32 v34, v34, v36
	v_add_f32_e32 v34, v35, v34
	v_mul_f32_e32 v39, 0x3fb8aa3b, v39
	v_mul_f32_e32 v34, 0x3fb8aa3b, v34
	v_exp_f32_e32 v44, v39
	v_cvt_pk_bf16_f32 v39, v53, v45
	v_cvt_pk_bf16_f32 v45, v58, v57
	v_exp_f32_e32 v57, v34
	v_sub_f32_e32 v34, v48, v167
	v_cndmask_b32_e64 v35, v189, v188, s[8:9]
	v_add_f32_e32 v34, v35, v34
	v_add_f32_e32 v34, v131, v34
	v_add_f32_e32 v34, v161, v34
	v_add_f32_e32 v35, v168, v34
	v_mul_f32_e32 v35, 0x3fb8aa3b, v35
	v_add_f32_e32 v34, v165, v34
	v_exp_f32_e32 v58, v35
	v_add_f32_e32 v35, v166, v34
	v_mul_f32_e32 v35, 0x3fb8aa3b, v35
	v_add_f32_e32 v34, v164, v34
	v_cvt_pk_bf16_f32 v44, v59, v44
	v_exp_f32_e32 v59, v35
	v_add_f32_e32 v35, v162, v34
	v_add_f32_e32 v34, v160, v34
	v_add_f32_e32 v34, v163, v34
	v_mul_f32_e32 v35, 0x3fb8aa3b, v35
	v_mul_f32_e32 v34, 0x3fb8aa3b, v34
	v_exp_f32_e32 v60, v35
	v_exp_f32_e32 v61, v34
	v_sub_f32_e32 v34, v47, v175
	v_cndmask_b32_e64 v35, v190, v189, s[8:9]
	v_add_f32_e32 v34, v35, v34
	v_add_f32_e32 v34, v131, v34
	v_add_f32_e32 v34, v46, v34
	v_mul_f32_e32 v55, 0x3fb8aa3b, v55
	v_add_f32_e32 v35, v176, v34
	v_add_f32_e32 v40, v137, v40
	v_exp_f32_e32 v55, v55
	v_mul_f32_e32 v35, 0x3fb8aa3b, v35
	v_add_f32_e32 v34, v173, v34
	v_mul_f32_e32 v51, 0x3fb8aa3b, v51
	v_mul_f32_e32 v40, 0x3fb8aa3b, v40
	v_mul_f32_e32 v43, 0x3fb8aa3b, v43
	v_mul_f32_e32 v54, 0x3fb8aa3b, v54
	v_exp_f32_e32 v62, v35
	v_add_f32_e32 v35, v174, v34
	v_add_f32_e32 v64, v171, v34
	v_add3_u32 v34, s81, v110, v111
	v_exp_f32_e32 v51, v51
	v_exp_f32_e32 v40, v40
	v_exp_f32_e32 v43, v43
	v_exp_f32_e32 v54, v54
	v_add_f32_e32 v50, v159, v49
	v_add_f32_e32 v49, v156, v37
	v_add_f32_e32 v37, v155, v36
	v_add3_u32 v46, v34, v119, v120
	v_mul_f32_e32 v37, 0x3fb8aa3b, v37
	v_mul_f32_e32 v35, 0x3fb8aa3b, v35
	v_add_u32_e32 v65, v46, v118
	v_cvt_pk_bf16_f32 v42, v56, v55
	v_exp_f32_e32 v56, v37
	v_exp_f32_e32 v63, v35
	ds_read_b64_tr_b16 v[34:35], v65 offset:8192
	ds_read_b64_tr_b16 v[36:37], v65 offset:9216
	v_add_f32_e32 v47, v172, v64
	v_mul_f32_e32 v50, 0x3fb8aa3b, v50
	v_mul_f32_e32 v49, 0x3fb8aa3b, v49
	v_mul_f32_e32 v47, 0x3fb8aa3b, v47
	v_add_u32_e32 v135, v46, v121
	v_cvt_pk_bf16_f32 v40, v40, v51
	v_cvt_pk_bf16_f32 v43, v54, v43
	v_exp_f32_e32 v54, v50
	v_exp_f32_e32 v55, v49
	v_exp_f32_e32 v134, v47
	ds_read_b64_tr_b16 v[46:47], v135 offset:8192
	ds_read_b64_tr_b16 v[48:49], v135 offset:9216
	ds_read_b64_tr_b16 v[50:51], v65 offset:10240
	ds_read_b64_tr_b16 v[52:53], v65 offset:11264
	s_waitcnt lgkmcnt(4)
	v_mfma_f32_32x32x16_bf16 v[18:33], v[34:37], v[38:41], v[18:33]
	v_add_f32_e32 v34, v169, v64
	v_add_f32_e32 v34, v170, v34
	v_mul_f32_e32 v34, 0x3fb8aa3b, v34
	v_exp_f32_e32 v64, v34
	ds_read_b64_tr_b16 v[34:35], v135 offset:10240
	ds_read_b64_tr_b16 v[36:37], v135 offset:11264
	v_sub_f32_e32 v136, v183, v183
	s_waitcnt lgkmcnt(4)
	v_mfma_f32_32x32x16_bf16 v[2:17], v[46:49], v[38:41], v[2:17]
	v_cndmask_b32_e64 v38, 0, v190, s[8:9]
	v_add_f32_e32 v38, v38, v136
	v_add_f32_e32 v38, v131, v38
	v_add_f32_e32 v0, v0, v38
	ds_read_b64_tr_b16 v[46:47], v65 offset:12288
	ds_read_b64_tr_b16 v[48:49], v65 offset:13312
	v_add_f32_e32 v38, v184, v0
	v_mul_f32_e32 v38, 0x3fb8aa3b, v38
	s_waitcnt lgkmcnt(4)
	v_mfma_f32_32x32x16_bf16 v[18:33], v[50:53], v[42:45], v[18:33]
	v_add_f32_e32 v0, v181, v0
	v_exp_f32_e32 v136, v38
	v_add_f32_e32 v38, v182, v0
	v_mul_f32_e32 v50, 0x3fb8aa3b, v38
	v_add_f32_e32 v0, v179, v0
	v_cvt_pk_bf16_f32 v38, v57, v56
	v_cvt_pk_bf16_f32 v39, v55, v54
	s_waitcnt lgkmcnt(2)
	v_mfma_f32_32x32x16_bf16 v[2:17], v[34:37], v[42:45], v[2:17]
	ds_read_b64_tr_b16 v[34:35], v135 offset:12288
	ds_read_b64_tr_b16 v[36:37], v135 offset:13312
	ds_read_b64_tr_b16 v[42:43], v65 offset:14336
	ds_read_b64_tr_b16 v[44:45], v65 offset:15360
	v_cvt_pk_bf16_f32 v40, v61, v60
	v_cvt_pk_bf16_f32 v41, v59, v58
	s_waitcnt lgkmcnt(4)
	s_nop 0
	v_mfma_f32_32x32x16_bf16 v[18:33], v[46:49], v[38:41], v[18:33]
	v_add_f32_e32 v46, v180, v0
	v_add_f32_e32 v0, v177, v0
	v_add_f32_e32 v0, v178, v0
	v_mul_f32_e32 v46, 0x3fb8aa3b, v46
	v_mul_f32_e32 v0, 0x3fb8aa3b, v0
	v_exp_f32_e32 v51, v46
	ds_read_b64_tr_b16 v[46:47], v135 offset:14336
	ds_read_b64_tr_b16 v[48:49], v135 offset:15360
	s_waitcnt lgkmcnt(4)
	v_mfma_f32_32x32x16_bf16 v[2:17], v[34:37], v[38:41], v[2:17]
	v_exp_f32_e32 v0, v0
	v_exp_f32_e32 v37, v50
	v_cvt_pk_bf16_f32 v34, v64, v134
	v_cvt_pk_bf16_f32 v35, v63, v62
	v_cvt_pk_bf16_f32 v36, v0, v51
	v_cvt_pk_bf16_f32 v37, v37, v136
	v_add_f32_e32 v0, v185, v186
	v_add_f32_e32 v131, v131, v0
	s_waitcnt lgkmcnt(2)
	v_mfma_f32_32x32x16_bf16 v[18:33], v[42:45], v[34:37], v[18:33]
	s_waitcnt lgkmcnt(0)
	v_mfma_f32_32x32x16_bf16 v[2:17], v[46:49], v[34:37], v[2:17]
